# speedup vs baseline: 1.0262x; 1.0134x over previous
.LBB0_572:
	s_lshl_b32 s2, s12, 8
	s_or_b32 s2, s2, s65
	v_and_b32_e32 v122, 1, v144
	v_mul_u32_u24_e32 v122, 12, v122
	v_lshl_add_u32 v122, v144, 2, v122
	v_add_u32_e32 v122, s2, v122
	v_ashrrev_i32_e32 v123, 31, v122
	v_lshl_add_u64 v[122:123], v[122:123], 1, s[18:19]
	v_mad_i64_i32 v[124:125], s[2:3], v132, s70, v[122:123]
	v_cvt_pk_bf16_f32 v126, v145, v147
	v_cvt_pk_bf16_f32 v127, v149, v152
	v_cvt_pk_bf16_f32 v128, v146, v148
	v_cvt_pk_bf16_f32 v129, v150, v151
	s_nop 1
	v_permlane16_swap_b32_e32 v126, v128
	v_permlane16_swap_b32_e32 v127, v129
	global_store_dwordx4 v[124:125], v[126:129], off
	s_nop 1
	v_mov_b32_e32 v135, v134
	v_mov_b32_e32 v126, v134
	v_mov_b32_e32 v127, v134
	v_pk_mul_f32 v[120:121], v[120:121], v[126:127]
	v_pk_mul_f32 v[118:119], v[118:119], v[134:135]
	v_pk_mul_f32 v[116:117], v[116:117], v[126:127]
	v_pk_mul_f32 v[114:115], v[114:115], v[134:135]
	s_cmp_gt_i32 s43, 1
	s_mov_b64 s[52:53], -1
	s_cbranch_scc0 .LBB0_574
	v_mul_f32_e32 v144, 0xbfb8aa3b, v121
	v_mul_f32_e32 v126, 0xbfb8aa3b, v118
	v_mul_f32_e32 v127, 0xbfb8aa3b, v114
	v_mul_f32_e32 v128, 0xbfb8aa3b, v119
	v_mul_f32_e32 v129, 0xbfb8aa3b, v115
	v_mul_f32_e32 v134, 0xbfb8aa3b, v120
	v_mul_f32_e32 v135, 0xbfb8aa3b, v116
	v_exp_f32_e32 v144, v144
	v_mul_f32_e32 v145, 0xbfb8aa3b, v117
	v_exp_f32_e32 v126, v126
	v_exp_f32_e32 v127, v127
	v_exp_f32_e32 v128, v128
	v_exp_f32_e32 v129, v129
	v_exp_f32_e32 v134, v134
	v_exp_f32_e32 v135, v135
	v_exp_f32_e32 v146, v145
	v_add_f32_e32 v144, 1.0, v144
	v_add_f32_e32 v126, 1.0, v126
	v_add_f32_e32 v127, 1.0, v127
	v_add_f32_e32 v128, 1.0, v128
	v_add_f32_e32 v129, 1.0, v129
	v_add_f32_e32 v134, 1.0, v134
	v_add_f32_e32 v135, 1.0, v135
	v_rcp_f32_e32 v145, v144
	v_add_f32_e32 v144, 1.0, v146
	v_rcp_f32_e32 v126, v126
	v_rcp_f32_e32 v127, v127
	v_rcp_f32_e32 v128, v128
	v_rcp_f32_e32 v129, v129
	v_rcp_f32_e32 v134, v134
	v_rcp_f32_e32 v135, v135
	v_rcp_f32_e32 v144, v144
	s_mov_b64 s[52:53], 0

.LBB0_578:
	v_cvt_pk_bf16_f32 v114, v126, v128
	v_cvt_pk_bf16_f32 v115, v134, v145
	v_cvt_pk_bf16_f32 v116, v127, v129
	v_cvt_pk_bf16_f32 v117, v135, v144
	s_nop 1
	v_permlane16_swap_b32_e32 v114, v116
	v_permlane16_swap_b32_e32 v115, v117
	global_store_dwordx4 v[124:125], v[114:117], off offset:256
	s_nop 1
	v_mul_f32_e32 v114, 0x3c800000, v143
	v_pk_mul_f32 v[112:113], v[112:113], v[114:115] op_sel_hi:[1,0]
	v_pk_mul_f32 v[110:111], v[110:111], v[114:115] op_sel_hi:[1,0]
	v_pk_mul_f32 v[108:109], v[108:109], v[114:115] op_sel_hi:[1,0]
	v_pk_mul_f32 v[106:107], v[106:107], v[114:115] op_sel_hi:[1,0]
	s_cmp_gt_i32 s43, 1
	s_mov_b64 s[52:53], -1
	s_cbranch_scc0 .LBB0_580
	v_mul_f32_e32 v115, 0xbfb8aa3b, v110
	v_exp_f32_e32 v115, v115
	v_mul_f32_e32 v116, 0xbfb8aa3b, v106
	v_exp_f32_e32 v116, v116
	v_mul_f32_e32 v118, 0xbfb8aa3b, v107
	v_add_f32_e32 v115, 1.0, v115
	v_exp_f32_e32 v119, v118
	v_add_f32_e32 v117, 1.0, v116
	v_rcp_f32_e32 v116, v115
	v_mul_f32_e32 v115, 0xbfb8aa3b, v111
	v_exp_f32_e32 v115, v115
	v_rcp_f32_e32 v117, v117
	s_mov_b64 s[52:53], 0
	v_add_f32_e32 v115, 1.0, v115
	v_rcp_f32_e32 v118, v115
	v_add_f32_e32 v115, 1.0, v119
	v_mul_f32_e32 v119, 0xbfb8aa3b, v112
	v_exp_f32_e32 v120, v119
	v_mul_f32_e32 v119, 0xbfb8aa3b, v108
	v_exp_f32_e32 v121, v119
	v_rcp_f32_e32 v119, v115
	v_add_f32_e32 v115, 1.0, v120
	v_rcp_f32_e32 v120, v115
	v_add_f32_e32 v115, 1.0, v121
	v_mul_f32_e32 v121, 0xbfb8aa3b, v113
	v_exp_f32_e32 v124, v121
	v_mul_f32_e32 v121, 0xbfb8aa3b, v109
	v_exp_f32_e32 v126, v121
	v_rcp_f32_e32 v121, v115
	v_add_f32_e32 v115, 1.0, v124
	v_rcp_f32_e32 v125, v115
	v_add_f32_e32 v115, 1.0, v126
	v_rcp_f32_e32 v124, v115

.LBB0_584:
	v_add_u32_e32 v106, 16, v132
	v_mad_i64_i32 v[106:107], s[2:3], v106, s70, v[122:123]
	v_cvt_pk_bf16_f32 v108, v116, v118
	v_cvt_pk_bf16_f32 v109, v120, v125
	v_cvt_pk_bf16_f32 v110, v117, v119
	v_cvt_pk_bf16_f32 v111, v121, v124
	s_nop 1
	v_permlane16_swap_b32_e32 v108, v110
	v_permlane16_swap_b32_e32 v109, v111
	global_store_dwordx4 v[106:107], v[108:111], off
	s_nop 1
	v_mov_b32_e32 v115, v114
	v_mov_b32_e32 v108, v114
	v_mov_b32_e32 v109, v114
	v_pk_mul_f32 v[104:105], v[104:105], v[108:109]
	v_pk_mul_f32 v[102:103], v[102:103], v[114:115]
	v_pk_mul_f32 v[100:101], v[100:101], v[108:109]
	v_pk_mul_f32 v[98:99], v[98:99], v[114:115]
	s_cmp_gt_i32 s43, 1
	s_mov_b64 s[52:53], -1
	s_cbranch_scc0 .LBB0_586
	v_mul_f32_e32 v114, 0xbfb8aa3b, v105
	v_mul_f32_e32 v108, 0xbfb8aa3b, v102
	v_mul_f32_e32 v109, 0xbfb8aa3b, v98
	v_mul_f32_e32 v110, 0xbfb8aa3b, v103
	v_mul_f32_e32 v111, 0xbfb8aa3b, v99
	v_mul_f32_e32 v112, 0xbfb8aa3b, v104
	v_mul_f32_e32 v113, 0xbfb8aa3b, v100
	v_exp_f32_e32 v114, v114
	v_mul_f32_e32 v115, 0xbfb8aa3b, v101
	v_exp_f32_e32 v108, v108
	v_exp_f32_e32 v109, v109
	v_exp_f32_e32 v110, v110
	v_exp_f32_e32 v111, v111
	v_exp_f32_e32 v112, v112
	v_exp_f32_e32 v113, v113
	v_exp_f32_e32 v116, v115
	v_add_f32_e32 v114, 1.0, v114
	v_add_f32_e32 v108, 1.0, v108
	v_add_f32_e32 v109, 1.0, v109
	v_add_f32_e32 v110, 1.0, v110
	v_add_f32_e32 v111, 1.0, v111
	v_add_f32_e32 v112, 1.0, v112
	v_add_f32_e32 v113, 1.0, v113
	v_rcp_f32_e32 v115, v114
	v_add_f32_e32 v114, 1.0, v116
	v_rcp_f32_e32 v108, v108
	v_rcp_f32_e32 v109, v109
	v_rcp_f32_e32 v110, v110
	v_rcp_f32_e32 v111, v111
	v_rcp_f32_e32 v112, v112
	v_rcp_f32_e32 v113, v113
	v_rcp_f32_e32 v114, v114
	s_mov_b64 s[52:53], 0

.LBB0_590:
	v_cvt_pk_bf16_f32 v98, v108, v110
	v_cvt_pk_bf16_f32 v99, v112, v115
	v_cvt_pk_bf16_f32 v100, v109, v111
	v_cvt_pk_bf16_f32 v101, v113, v114
	s_nop 1
	v_permlane16_swap_b32_e32 v98, v100
	v_permlane16_swap_b32_e32 v99, v101
	global_store_dwordx4 v[106:107], v[98:101], off offset:256
	s_nop 1
	v_mul_f32_e32 v98, 0x3c800000, v142
	v_pk_mul_f32 v[96:97], v[96:97], v[98:99] op_sel_hi:[1,0]
	v_pk_mul_f32 v[94:95], v[94:95], v[98:99] op_sel_hi:[1,0]
	v_pk_mul_f32 v[92:93], v[92:93], v[98:99] op_sel_hi:[1,0]
	v_pk_mul_f32 v[90:91], v[90:91], v[98:99] op_sel_hi:[1,0]
	s_cmp_gt_i32 s43, 1
	s_mov_b64 s[52:53], -1
	s_cbranch_scc0 .LBB0_592
	v_mul_f32_e32 v99, 0xbfb8aa3b, v94
	v_exp_f32_e32 v99, v99
	v_mul_f32_e32 v100, 0xbfb8aa3b, v90
	v_exp_f32_e32 v100, v100
	v_mul_f32_e32 v102, 0xbfb8aa3b, v91
	v_add_f32_e32 v99, 1.0, v99
	v_exp_f32_e32 v103, v102
	v_add_f32_e32 v101, 1.0, v100
	v_rcp_f32_e32 v100, v99
	v_mul_f32_e32 v99, 0xbfb8aa3b, v95
	v_exp_f32_e32 v99, v99
	v_rcp_f32_e32 v101, v101
	s_mov_b64 s[52:53], 0
	v_add_f32_e32 v99, 1.0, v99
	v_rcp_f32_e32 v102, v99
	v_add_f32_e32 v99, 1.0, v103
	v_mul_f32_e32 v103, 0xbfb8aa3b, v96
	v_exp_f32_e32 v104, v103
	v_mul_f32_e32 v103, 0xbfb8aa3b, v92
	v_exp_f32_e32 v105, v103
	v_rcp_f32_e32 v103, v99
	v_add_f32_e32 v99, 1.0, v104
	v_rcp_f32_e32 v104, v99
	v_add_f32_e32 v99, 1.0, v105
	v_mul_f32_e32 v105, 0xbfb8aa3b, v97
	v_exp_f32_e32 v106, v105
	v_mul_f32_e32 v105, 0xbfb8aa3b, v93
	v_exp_f32_e32 v108, v105
	v_rcp_f32_e32 v105, v99
	v_add_f32_e32 v99, 1.0, v106
	v_rcp_f32_e32 v107, v99
	v_add_f32_e32 v99, 1.0, v108
	v_rcp_f32_e32 v106, v99

.LBB0_596:
	v_add_u32_e32 v90, 32, v132
	v_mad_i64_i32 v[90:91], s[2:3], v90, s70, v[122:123]
	v_cvt_pk_bf16_f32 v92, v100, v102
	v_cvt_pk_bf16_f32 v93, v104, v107
	v_cvt_pk_bf16_f32 v94, v101, v103
	v_cvt_pk_bf16_f32 v95, v105, v106
	s_nop 1
	v_permlane16_swap_b32_e32 v92, v94
	v_permlane16_swap_b32_e32 v93, v95
	global_store_dwordx4 v[90:91], v[92:95], off
	s_nop 1
	v_mov_b32_e32 v99, v98
	v_mov_b32_e32 v92, v98
	v_mov_b32_e32 v93, v98
	v_pk_mul_f32 v[88:89], v[88:89], v[92:93]
	v_pk_mul_f32 v[86:87], v[86:87], v[98:99]
	v_pk_mul_f32 v[84:85], v[84:85], v[92:93]
	v_pk_mul_f32 v[82:83], v[82:83], v[98:99]
	s_cmp_gt_i32 s43, 1
	s_mov_b64 s[52:53], -1
	s_cbranch_scc0 .LBB0_598
	v_mul_f32_e32 v98, 0xbfb8aa3b, v89
	v_mul_f32_e32 v92, 0xbfb8aa3b, v86
	v_mul_f32_e32 v93, 0xbfb8aa3b, v82
	v_mul_f32_e32 v94, 0xbfb8aa3b, v87
	v_mul_f32_e32 v95, 0xbfb8aa3b, v83
	v_mul_f32_e32 v96, 0xbfb8aa3b, v88
	v_mul_f32_e32 v97, 0xbfb8aa3b, v84
	v_exp_f32_e32 v98, v98
	v_mul_f32_e32 v99, 0xbfb8aa3b, v85
	v_exp_f32_e32 v92, v92
	v_exp_f32_e32 v93, v93
	v_exp_f32_e32 v94, v94
	v_exp_f32_e32 v95, v95
	v_exp_f32_e32 v96, v96
	v_exp_f32_e32 v97, v97
	v_exp_f32_e32 v100, v99
	v_add_f32_e32 v98, 1.0, v98
	v_add_f32_e32 v92, 1.0, v92
	v_add_f32_e32 v93, 1.0, v93
	v_add_f32_e32 v94, 1.0, v94
	v_add_f32_e32 v95, 1.0, v95
	v_add_f32_e32 v96, 1.0, v96
	v_add_f32_e32 v97, 1.0, v97
	v_rcp_f32_e32 v99, v98
	v_add_f32_e32 v98, 1.0, v100
	v_rcp_f32_e32 v92, v92
	v_rcp_f32_e32 v93, v93
	v_rcp_f32_e32 v94, v94
	v_rcp_f32_e32 v95, v95
	v_rcp_f32_e32 v96, v96
	v_rcp_f32_e32 v97, v97
	v_rcp_f32_e32 v98, v98
	s_mov_b64 s[52:53], 0

.LBB0_602:
	v_cvt_pk_bf16_f32 v82, v92, v94
	v_cvt_pk_bf16_f32 v83, v96, v99
	v_cvt_pk_bf16_f32 v84, v93, v95
	v_cvt_pk_bf16_f32 v85, v97, v98
	s_nop 1
	v_permlane16_swap_b32_e32 v82, v84
	v_permlane16_swap_b32_e32 v83, v85
	global_store_dwordx4 v[90:91], v[82:85], off offset:256
	s_nop 1
	v_mul_f32_e32 v82, 0x3c800000, v141
	v_pk_mul_f32 v[80:81], v[80:81], v[82:83] op_sel_hi:[1,0]
	v_pk_mul_f32 v[78:79], v[78:79], v[82:83] op_sel_hi:[1,0]
	v_pk_mul_f32 v[76:77], v[76:77], v[82:83] op_sel_hi:[1,0]
	v_pk_mul_f32 v[74:75], v[74:75], v[82:83] op_sel_hi:[1,0]
	s_cmp_gt_i32 s43, 1
	s_mov_b64 s[52:53], -1
	s_cbranch_scc0 .LBB0_604
	v_mul_f32_e32 v83, 0xbfb8aa3b, v78
	v_exp_f32_e32 v83, v83
	v_mul_f32_e32 v84, 0xbfb8aa3b, v74
	v_exp_f32_e32 v84, v84
	v_mul_f32_e32 v86, 0xbfb8aa3b, v75
	v_add_f32_e32 v83, 1.0, v83
	v_exp_f32_e32 v87, v86
	v_add_f32_e32 v85, 1.0, v84
	v_rcp_f32_e32 v84, v83
	v_mul_f32_e32 v83, 0xbfb8aa3b, v79
	v_exp_f32_e32 v83, v83
	v_rcp_f32_e32 v85, v85
	s_mov_b64 s[52:53], 0
	v_add_f32_e32 v83, 1.0, v83
	v_rcp_f32_e32 v86, v83
	v_add_f32_e32 v83, 1.0, v87
	v_mul_f32_e32 v87, 0xbfb8aa3b, v80
	v_exp_f32_e32 v88, v87
	v_mul_f32_e32 v87, 0xbfb8aa3b, v76
	v_exp_f32_e32 v89, v87
	v_rcp_f32_e32 v87, v83
	v_add_f32_e32 v83, 1.0, v88
	v_rcp_f32_e32 v88, v83
	v_add_f32_e32 v83, 1.0, v89
	v_mul_f32_e32 v89, 0xbfb8aa3b, v81
	v_exp_f32_e32 v90, v89
	v_mul_f32_e32 v89, 0xbfb8aa3b, v77
	v_exp_f32_e32 v92, v89
	v_rcp_f32_e32 v89, v83
	v_add_f32_e32 v83, 1.0, v90
	v_rcp_f32_e32 v91, v83
	v_add_f32_e32 v83, 1.0, v92
	v_rcp_f32_e32 v90, v83

.LBB0_608:
	v_add_u32_e32 v74, 48, v132
	v_mad_i64_i32 v[74:75], s[2:3], v74, s70, v[122:123]
	v_cvt_pk_bf16_f32 v76, v84, v86
	v_cvt_pk_bf16_f32 v77, v88, v91
	v_cvt_pk_bf16_f32 v78, v85, v87
	v_cvt_pk_bf16_f32 v79, v89, v90
	s_nop 1
	v_permlane16_swap_b32_e32 v76, v78
	v_permlane16_swap_b32_e32 v77, v79
	global_store_dwordx4 v[74:75], v[76:79], off
	s_nop 1
	v_mov_b32_e32 v83, v82
	v_mov_b32_e32 v76, v82
	v_mov_b32_e32 v77, v82
	v_pk_mul_f32 v[72:73], v[72:73], v[76:77]
	v_pk_mul_f32 v[70:71], v[70:71], v[82:83]
	v_pk_mul_f32 v[68:69], v[68:69], v[76:77]
	v_pk_mul_f32 v[66:67], v[66:67], v[82:83]
	s_cmp_gt_i32 s43, 1
	s_mov_b64 s[52:53], -1
	s_cbranch_scc0 .LBB0_610
	v_mul_f32_e32 v82, 0xbfb8aa3b, v73
	v_mul_f32_e32 v76, 0xbfb8aa3b, v70
	v_mul_f32_e32 v77, 0xbfb8aa3b, v66
	v_mul_f32_e32 v78, 0xbfb8aa3b, v71
	v_mul_f32_e32 v79, 0xbfb8aa3b, v67
	v_mul_f32_e32 v80, 0xbfb8aa3b, v72
	v_mul_f32_e32 v81, 0xbfb8aa3b, v68
	v_exp_f32_e32 v82, v82
	v_mul_f32_e32 v83, 0xbfb8aa3b, v69
	v_exp_f32_e32 v76, v76
	v_exp_f32_e32 v77, v77
	v_exp_f32_e32 v78, v78
	v_exp_f32_e32 v79, v79
	v_exp_f32_e32 v80, v80
	v_exp_f32_e32 v81, v81
	v_exp_f32_e32 v84, v83
	v_add_f32_e32 v82, 1.0, v82
	v_add_f32_e32 v76, 1.0, v76
	v_add_f32_e32 v77, 1.0, v77
	v_add_f32_e32 v78, 1.0, v78
	v_add_f32_e32 v79, 1.0, v79
	v_add_f32_e32 v80, 1.0, v80
	v_add_f32_e32 v81, 1.0, v81
	v_rcp_f32_e32 v83, v82
	v_add_f32_e32 v82, 1.0, v84
	v_rcp_f32_e32 v76, v76
	v_rcp_f32_e32 v77, v77
	v_rcp_f32_e32 v78, v78
	v_rcp_f32_e32 v79, v79
	v_rcp_f32_e32 v80, v80
	v_rcp_f32_e32 v81, v81
	v_rcp_f32_e32 v82, v82
	s_mov_b64 s[52:53], 0

.LBB0_614:
	v_cvt_pk_bf16_f32 v66, v76, v78
	v_cvt_pk_bf16_f32 v67, v80, v83
	v_cvt_pk_bf16_f32 v68, v77, v79
	v_cvt_pk_bf16_f32 v69, v81, v82
	s_nop 1
	v_permlane16_swap_b32_e32 v66, v68
	v_permlane16_swap_b32_e32 v67, v69
	global_store_dwordx4 v[74:75], v[66:69], off offset:256
	s_nop 1
	v_mul_f32_e32 v66, 0x3c800000, v140
	v_pk_mul_f32 v[64:65], v[64:65], v[66:67] op_sel_hi:[1,0]
	v_pk_mul_f32 v[62:63], v[62:63], v[66:67] op_sel_hi:[1,0]
	v_pk_mul_f32 v[60:61], v[60:61], v[66:67] op_sel_hi:[1,0]
	v_pk_mul_f32 v[58:59], v[58:59], v[66:67] op_sel_hi:[1,0]
	s_cmp_gt_i32 s43, 1
	s_mov_b64 s[52:53], -1
	s_cbranch_scc0 .LBB0_616
	v_mul_f32_e32 v67, 0xbfb8aa3b, v62
	v_exp_f32_e32 v67, v67
	v_mul_f32_e32 v68, 0xbfb8aa3b, v58
	v_exp_f32_e32 v68, v68
	v_mul_f32_e32 v70, 0xbfb8aa3b, v59
	v_add_f32_e32 v67, 1.0, v67
	v_exp_f32_e32 v71, v70
	v_add_f32_e32 v69, 1.0, v68
	v_rcp_f32_e32 v68, v67
	v_mul_f32_e32 v67, 0xbfb8aa3b, v63
	v_exp_f32_e32 v67, v67
	v_rcp_f32_e32 v69, v69
	s_mov_b64 s[52:53], 0
	v_add_f32_e32 v67, 1.0, v67
	v_rcp_f32_e32 v70, v67
	v_add_f32_e32 v67, 1.0, v71
	v_mul_f32_e32 v71, 0xbfb8aa3b, v64
	v_exp_f32_e32 v72, v71
	v_mul_f32_e32 v71, 0xbfb8aa3b, v60
	v_exp_f32_e32 v73, v71
	v_rcp_f32_e32 v71, v67
	v_add_f32_e32 v67, 1.0, v72
	v_rcp_f32_e32 v72, v67
	v_add_f32_e32 v67, 1.0, v73
	v_mul_f32_e32 v73, 0xbfb8aa3b, v65
	v_exp_f32_e32 v74, v73
	v_mul_f32_e32 v73, 0xbfb8aa3b, v61
	v_exp_f32_e32 v76, v73
	v_rcp_f32_e32 v73, v67
	v_add_f32_e32 v67, 1.0, v74
	v_rcp_f32_e32 v75, v67
	v_add_f32_e32 v67, 1.0, v76
	v_rcp_f32_e32 v74, v67

.LBB0_620:
	v_add_u32_e32 v58, 0x80, v132
	v_mad_i64_i32 v[58:59], s[2:3], v58, s70, v[122:123]
	v_cvt_pk_bf16_f32 v60, v68, v70
	v_cvt_pk_bf16_f32 v61, v72, v75
	v_cvt_pk_bf16_f32 v62, v69, v71
	v_cvt_pk_bf16_f32 v63, v73, v74
	s_nop 1
	v_permlane16_swap_b32_e32 v60, v62
	v_permlane16_swap_b32_e32 v61, v63
	global_store_dwordx4 v[58:59], v[60:63], off
	s_nop 1
	v_mov_b32_e32 v67, v66
	v_mov_b32_e32 v60, v66
	v_mov_b32_e32 v61, v66
	v_pk_mul_f32 v[56:57], v[56:57], v[60:61]
	v_pk_mul_f32 v[54:55], v[54:55], v[66:67]
	v_pk_mul_f32 v[52:53], v[52:53], v[60:61]
	v_pk_mul_f32 v[50:51], v[50:51], v[66:67]
	s_cmp_gt_i32 s43, 1
	s_mov_b64 s[52:53], -1
	s_cbranch_scc0 .LBB0_622
	v_mul_f32_e32 v66, 0xbfb8aa3b, v57
	v_mul_f32_e32 v60, 0xbfb8aa3b, v54
	v_mul_f32_e32 v61, 0xbfb8aa3b, v50
	v_mul_f32_e32 v62, 0xbfb8aa3b, v55
	v_mul_f32_e32 v63, 0xbfb8aa3b, v51
	v_mul_f32_e32 v64, 0xbfb8aa3b, v56
	v_mul_f32_e32 v65, 0xbfb8aa3b, v52
	v_exp_f32_e32 v66, v66
	v_mul_f32_e32 v67, 0xbfb8aa3b, v53
	v_exp_f32_e32 v60, v60
	v_exp_f32_e32 v61, v61
	v_exp_f32_e32 v62, v62
	v_exp_f32_e32 v63, v63
	v_exp_f32_e32 v64, v64
	v_exp_f32_e32 v65, v65
	v_exp_f32_e32 v68, v67
	v_add_f32_e32 v66, 1.0, v66
	v_add_f32_e32 v60, 1.0, v60
	v_add_f32_e32 v61, 1.0, v61
	v_add_f32_e32 v62, 1.0, v62
	v_add_f32_e32 v63, 1.0, v63
	v_add_f32_e32 v64, 1.0, v64
	v_add_f32_e32 v65, 1.0, v65
	v_rcp_f32_e32 v67, v66
	v_add_f32_e32 v66, 1.0, v68
	v_rcp_f32_e32 v60, v60
	v_rcp_f32_e32 v61, v61
	v_rcp_f32_e32 v62, v62
	v_rcp_f32_e32 v63, v63
	v_rcp_f32_e32 v64, v64
	v_rcp_f32_e32 v65, v65
	v_rcp_f32_e32 v66, v66
	s_mov_b64 s[52:53], 0

.LBB0_626:
	v_cvt_pk_bf16_f32 v50, v60, v62
	v_cvt_pk_bf16_f32 v51, v64, v67
	v_cvt_pk_bf16_f32 v52, v61, v63
	v_cvt_pk_bf16_f32 v53, v65, v66
	s_nop 1
	v_permlane16_swap_b32_e32 v50, v52
	v_permlane16_swap_b32_e32 v51, v53
	global_store_dwordx4 v[58:59], v[50:53], off offset:256
	s_nop 1
	v_mul_f32_e32 v50, 0x3c800000, v139
	v_pk_mul_f32 v[48:49], v[48:49], v[50:51] op_sel_hi:[1,0]
	v_pk_mul_f32 v[46:47], v[46:47], v[50:51] op_sel_hi:[1,0]
	v_pk_mul_f32 v[44:45], v[44:45], v[50:51] op_sel_hi:[1,0]
	v_pk_mul_f32 v[42:43], v[42:43], v[50:51] op_sel_hi:[1,0]
	s_cmp_gt_i32 s43, 1
	s_mov_b64 s[52:53], -1
	s_cbranch_scc0 .LBB0_628
	v_mul_f32_e32 v51, 0xbfb8aa3b, v46
	v_exp_f32_e32 v51, v51
	v_mul_f32_e32 v52, 0xbfb8aa3b, v42
	v_exp_f32_e32 v52, v52
	v_mul_f32_e32 v54, 0xbfb8aa3b, v43
	v_add_f32_e32 v51, 1.0, v51
	v_exp_f32_e32 v55, v54
	v_add_f32_e32 v53, 1.0, v52
	v_rcp_f32_e32 v52, v51
	v_mul_f32_e32 v51, 0xbfb8aa3b, v47
	v_exp_f32_e32 v51, v51
	v_rcp_f32_e32 v53, v53
	s_mov_b64 s[52:53], 0
	v_add_f32_e32 v51, 1.0, v51
	v_rcp_f32_e32 v54, v51
	v_add_f32_e32 v51, 1.0, v55
	v_mul_f32_e32 v55, 0xbfb8aa3b, v48
	v_exp_f32_e32 v56, v55
	v_mul_f32_e32 v55, 0xbfb8aa3b, v44
	v_exp_f32_e32 v57, v55
	v_rcp_f32_e32 v55, v51
	v_add_f32_e32 v51, 1.0, v56
	v_rcp_f32_e32 v56, v51
	v_add_f32_e32 v51, 1.0, v57
	v_mul_f32_e32 v57, 0xbfb8aa3b, v49
	v_exp_f32_e32 v58, v57
	v_mul_f32_e32 v57, 0xbfb8aa3b, v45
	v_exp_f32_e32 v60, v57
	v_rcp_f32_e32 v57, v51
	v_add_f32_e32 v51, 1.0, v58
	v_rcp_f32_e32 v59, v51
	v_add_f32_e32 v51, 1.0, v60
	v_rcp_f32_e32 v58, v51

.LBB0_632:
	v_add_u32_e32 v42, 0x90, v132
	v_mad_i64_i32 v[42:43], s[2:3], v42, s70, v[122:123]
	v_cvt_pk_bf16_f32 v44, v52, v54
	v_cvt_pk_bf16_f32 v45, v56, v59
	v_cvt_pk_bf16_f32 v46, v53, v55
	v_cvt_pk_bf16_f32 v47, v57, v58
	s_nop 1
	v_permlane16_swap_b32_e32 v44, v46
	v_permlane16_swap_b32_e32 v45, v47
	global_store_dwordx4 v[42:43], v[44:47], off
	s_nop 1
	v_mov_b32_e32 v51, v50
	v_mov_b32_e32 v44, v50
	v_mov_b32_e32 v45, v50
	v_pk_mul_f32 v[40:41], v[40:41], v[44:45]
	v_pk_mul_f32 v[38:39], v[38:39], v[50:51]
	v_pk_mul_f32 v[36:37], v[36:37], v[44:45]
	v_pk_mul_f32 v[34:35], v[34:35], v[50:51]
	s_cmp_gt_i32 s43, 1
	s_mov_b64 s[52:53], -1
	s_cbranch_scc0 .LBB0_634
	v_mul_f32_e32 v50, 0xbfb8aa3b, v41
	v_mul_f32_e32 v44, 0xbfb8aa3b, v38
	v_mul_f32_e32 v45, 0xbfb8aa3b, v34
	v_mul_f32_e32 v46, 0xbfb8aa3b, v39
	v_mul_f32_e32 v47, 0xbfb8aa3b, v35
	v_mul_f32_e32 v48, 0xbfb8aa3b, v40
	v_mul_f32_e32 v49, 0xbfb8aa3b, v36
	v_exp_f32_e32 v50, v50
	v_mul_f32_e32 v51, 0xbfb8aa3b, v37
	v_exp_f32_e32 v44, v44
	v_exp_f32_e32 v45, v45
	v_exp_f32_e32 v46, v46
	v_exp_f32_e32 v47, v47
	v_exp_f32_e32 v48, v48
	v_exp_f32_e32 v49, v49
	v_exp_f32_e32 v52, v51
	v_add_f32_e32 v50, 1.0, v50
	v_add_f32_e32 v44, 1.0, v44
	v_add_f32_e32 v45, 1.0, v45
	v_add_f32_e32 v46, 1.0, v46
	v_add_f32_e32 v47, 1.0, v47
	v_add_f32_e32 v48, 1.0, v48
	v_add_f32_e32 v49, 1.0, v49
	v_rcp_f32_e32 v51, v50
	v_add_f32_e32 v50, 1.0, v52
	v_rcp_f32_e32 v44, v44
	v_rcp_f32_e32 v45, v45
	v_rcp_f32_e32 v46, v46
	v_rcp_f32_e32 v47, v47
	v_rcp_f32_e32 v48, v48
	v_rcp_f32_e32 v49, v49
	v_rcp_f32_e32 v50, v50
	s_mov_b64 s[52:53], 0

.LBB0_638:
	v_cvt_pk_bf16_f32 v34, v44, v46
	v_cvt_pk_bf16_f32 v35, v48, v51
	v_cvt_pk_bf16_f32 v36, v45, v47
	v_cvt_pk_bf16_f32 v37, v49, v50
	s_nop 1
	v_permlane16_swap_b32_e32 v34, v36
	v_permlane16_swap_b32_e32 v35, v37
	global_store_dwordx4 v[42:43], v[34:37], off offset:256
	s_nop 1
	v_mul_f32_e32 v34, 0x3c800000, v138
	v_pk_mul_f32 v[32:33], v[32:33], v[34:35] op_sel_hi:[1,0]
	v_pk_mul_f32 v[30:31], v[30:31], v[34:35] op_sel_hi:[1,0]
	v_pk_mul_f32 v[28:29], v[28:29], v[34:35] op_sel_hi:[1,0]
	v_pk_mul_f32 v[26:27], v[26:27], v[34:35] op_sel_hi:[1,0]
	s_cmp_gt_i32 s43, 1
	s_mov_b64 s[52:53], -1
	s_cbranch_scc0 .LBB0_640
	v_mul_f32_e32 v35, 0xbfb8aa3b, v30
	v_exp_f32_e32 v35, v35
	v_mul_f32_e32 v36, 0xbfb8aa3b, v26
	v_exp_f32_e32 v36, v36
	v_mul_f32_e32 v38, 0xbfb8aa3b, v27
	v_add_f32_e32 v35, 1.0, v35
	v_exp_f32_e32 v39, v38
	v_add_f32_e32 v37, 1.0, v36
	v_rcp_f32_e32 v36, v35
	v_mul_f32_e32 v35, 0xbfb8aa3b, v31
	v_exp_f32_e32 v35, v35
	v_rcp_f32_e32 v37, v37
	s_mov_b64 s[52:53], 0
	v_add_f32_e32 v35, 1.0, v35
	v_rcp_f32_e32 v38, v35
	v_add_f32_e32 v35, 1.0, v39
	v_mul_f32_e32 v39, 0xbfb8aa3b, v32
	v_exp_f32_e32 v40, v39
	v_mul_f32_e32 v39, 0xbfb8aa3b, v28
	v_exp_f32_e32 v41, v39
	v_rcp_f32_e32 v39, v35
	v_add_f32_e32 v35, 1.0, v40
	v_rcp_f32_e32 v40, v35
	v_add_f32_e32 v35, 1.0, v41
	v_mul_f32_e32 v41, 0xbfb8aa3b, v33
	v_exp_f32_e32 v42, v41
	v_mul_f32_e32 v41, 0xbfb8aa3b, v29
	v_exp_f32_e32 v44, v41
	v_rcp_f32_e32 v41, v35
	v_add_f32_e32 v35, 1.0, v42
	v_rcp_f32_e32 v43, v35
	v_add_f32_e32 v35, 1.0, v44
	v_rcp_f32_e32 v42, v35

.LBB0_644:
	v_add_u32_e32 v26, 0xa0, v132
	v_mad_i64_i32 v[26:27], s[2:3], v26, s70, v[122:123]
	v_cvt_pk_bf16_f32 v28, v36, v38
	v_cvt_pk_bf16_f32 v29, v40, v43
	v_cvt_pk_bf16_f32 v30, v37, v39
	v_cvt_pk_bf16_f32 v31, v41, v42
	s_nop 1
	v_permlane16_swap_b32_e32 v28, v30
	v_permlane16_swap_b32_e32 v29, v31
	global_store_dwordx4 v[26:27], v[28:31], off
	s_nop 1
	v_mov_b32_e32 v35, v34
	v_mov_b32_e32 v28, v34
	v_mov_b32_e32 v29, v34
	v_pk_mul_f32 v[24:25], v[24:25], v[28:29]
	v_pk_mul_f32 v[22:23], v[22:23], v[34:35]
	v_pk_mul_f32 v[20:21], v[20:21], v[28:29]
	v_pk_mul_f32 v[18:19], v[18:19], v[34:35]
	s_cmp_gt_i32 s43, 1
	s_mov_b64 s[52:53], -1
	s_cbranch_scc0 .LBB0_646
	v_mul_f32_e32 v34, 0xbfb8aa3b, v25
	v_mul_f32_e32 v28, 0xbfb8aa3b, v22
	v_mul_f32_e32 v29, 0xbfb8aa3b, v18
	v_mul_f32_e32 v30, 0xbfb8aa3b, v23
	v_mul_f32_e32 v31, 0xbfb8aa3b, v19
	v_mul_f32_e32 v32, 0xbfb8aa3b, v24
	v_mul_f32_e32 v33, 0xbfb8aa3b, v20
	v_exp_f32_e32 v34, v34
	v_mul_f32_e32 v35, 0xbfb8aa3b, v21
	v_exp_f32_e32 v28, v28
	v_exp_f32_e32 v29, v29
	v_exp_f32_e32 v30, v30
	v_exp_f32_e32 v31, v31
	v_exp_f32_e32 v32, v32
	v_exp_f32_e32 v33, v33
	v_exp_f32_e32 v36, v35
	v_add_f32_e32 v34, 1.0, v34
	v_add_f32_e32 v28, 1.0, v28
	v_add_f32_e32 v29, 1.0, v29
	v_add_f32_e32 v30, 1.0, v30
	v_add_f32_e32 v31, 1.0, v31
	v_add_f32_e32 v32, 1.0, v32
	v_add_f32_e32 v33, 1.0, v33
	v_rcp_f32_e32 v35, v34
	v_add_f32_e32 v34, 1.0, v36
	v_rcp_f32_e32 v28, v28
	v_rcp_f32_e32 v29, v29
	v_rcp_f32_e32 v30, v30
	v_rcp_f32_e32 v31, v31
	v_rcp_f32_e32 v32, v32
	v_rcp_f32_e32 v33, v33
	v_rcp_f32_e32 v34, v34
	s_mov_b64 s[52:53], 0

.LBB0_650:
	v_cvt_pk_bf16_f32 v18, v28, v30
	v_cvt_pk_bf16_f32 v19, v32, v35
	v_cvt_pk_bf16_f32 v20, v29, v31
	v_cvt_pk_bf16_f32 v21, v33, v34
	s_nop 1
	v_permlane16_swap_b32_e32 v18, v20
	v_permlane16_swap_b32_e32 v19, v21
	global_store_dwordx4 v[26:27], v[18:21], off offset:256
	s_nop 1
	v_mul_f32_e32 v18, 0x3c800000, v133
	v_pk_mul_f32 v[16:17], v[16:17], v[18:19] op_sel_hi:[1,0]
	v_pk_mul_f32 v[14:15], v[14:15], v[18:19] op_sel_hi:[1,0]
	v_pk_mul_f32 v[12:13], v[12:13], v[18:19] op_sel_hi:[1,0]
	v_pk_mul_f32 v[10:11], v[10:11], v[18:19] op_sel_hi:[1,0]
	s_cmp_gt_i32 s43, 1
	s_mov_b64 s[52:53], -1
	s_cbranch_scc0 .LBB0_652
	v_mul_f32_e32 v19, 0xbfb8aa3b, v14
	v_exp_f32_e32 v19, v19
	v_mul_f32_e32 v20, 0xbfb8aa3b, v10
	v_exp_f32_e32 v20, v20
	v_mul_f32_e32 v22, 0xbfb8aa3b, v11
	v_add_f32_e32 v19, 1.0, v19
	v_exp_f32_e32 v23, v22
	v_add_f32_e32 v21, 1.0, v20
	v_rcp_f32_e32 v20, v19
	v_mul_f32_e32 v19, 0xbfb8aa3b, v15
	v_exp_f32_e32 v19, v19
	v_rcp_f32_e32 v21, v21
	s_mov_b64 s[52:53], 0
	v_add_f32_e32 v19, 1.0, v19
	v_rcp_f32_e32 v22, v19
	v_add_f32_e32 v19, 1.0, v23
	v_mul_f32_e32 v23, 0xbfb8aa3b, v16
	v_exp_f32_e32 v24, v23
	v_mul_f32_e32 v23, 0xbfb8aa3b, v12
	v_exp_f32_e32 v25, v23
	v_rcp_f32_e32 v23, v19
	v_add_f32_e32 v19, 1.0, v24
	v_rcp_f32_e32 v24, v19
	v_add_f32_e32 v19, 1.0, v25
	v_mul_f32_e32 v25, 0xbfb8aa3b, v17
	v_exp_f32_e32 v26, v25
	v_mul_f32_e32 v25, 0xbfb8aa3b, v13
	v_exp_f32_e32 v28, v25
	v_rcp_f32_e32 v25, v19
	v_add_f32_e32 v19, 1.0, v26
	v_rcp_f32_e32 v27, v19
	v_add_f32_e32 v19, 1.0, v28
	v_rcp_f32_e32 v26, v19

.LBB0_656:
	v_add_u32_e32 v10, 0xb0, v132
	v_mad_i64_i32 v[10:11], s[2:3], v10, s70, v[122:123]
	v_cvt_pk_bf16_f32 v12, v20, v22
	v_cvt_pk_bf16_f32 v13, v24, v27
	v_cvt_pk_bf16_f32 v14, v21, v23
	v_cvt_pk_bf16_f32 v15, v25, v26
	s_nop 1
	v_permlane16_swap_b32_e32 v12, v14
	v_permlane16_swap_b32_e32 v13, v15
	global_store_dwordx4 v[10:11], v[12:15], off
	s_nop 1
	v_mov_b32_e32 v19, v18
	v_mov_b32_e32 v12, v18
	v_mov_b32_e32 v13, v18
	v_pk_mul_f32 v[8:9], v[8:9], v[12:13]
	v_pk_mul_f32 v[6:7], v[6:7], v[18:19]
	v_pk_mul_f32 v[4:5], v[4:5], v[12:13]
	v_pk_mul_f32 v[2:3], v[2:3], v[18:19]
	s_cmp_gt_i32 s43, 1
	s_mov_b64 s[52:53], -1
	s_cbranch_scc0 .LBB0_658
	v_mul_f32_e32 v18, 0xbfb8aa3b, v9
	v_mul_f32_e32 v12, 0xbfb8aa3b, v6
	v_mul_f32_e32 v13, 0xbfb8aa3b, v2
	v_mul_f32_e32 v14, 0xbfb8aa3b, v7
	v_mul_f32_e32 v15, 0xbfb8aa3b, v3
	v_mul_f32_e32 v16, 0xbfb8aa3b, v8
	v_mul_f32_e32 v17, 0xbfb8aa3b, v4
	v_exp_f32_e32 v18, v18
	v_mul_f32_e32 v19, 0xbfb8aa3b, v5
	v_exp_f32_e32 v12, v12
	v_exp_f32_e32 v13, v13
	v_exp_f32_e32 v14, v14
	v_exp_f32_e32 v15, v15
	v_exp_f32_e32 v16, v16
	v_exp_f32_e32 v17, v17
	v_exp_f32_e32 v20, v19
	v_add_f32_e32 v18, 1.0, v18
	v_add_f32_e32 v12, 1.0, v12
	v_add_f32_e32 v13, 1.0, v13
	v_add_f32_e32 v14, 1.0, v14
	v_add_f32_e32 v15, 1.0, v15
	v_add_f32_e32 v16, 1.0, v16
	v_add_f32_e32 v17, 1.0, v17
	v_rcp_f32_e32 v19, v18
	v_add_f32_e32 v18, 1.0, v20
	v_rcp_f32_e32 v12, v12
	v_rcp_f32_e32 v13, v13
	v_rcp_f32_e32 v14, v14
	v_rcp_f32_e32 v15, v15
	v_rcp_f32_e32 v16, v16
	v_rcp_f32_e32 v17, v17
	v_rcp_f32_e32 v18, v18
	s_mov_b64 s[52:53], 0

.LBB0_662:
	v_cvt_pk_bf16_f32 v2, v12, v14
	v_cvt_pk_bf16_f32 v3, v16, v19
	s_andn2_b64 vcc, exec, s[38:39]
	s_mov_b64 s[38:39], -1
	v_cvt_pk_bf16_f32 v4, v13, v15
	v_cvt_pk_bf16_f32 v5, v17, v18
	s_nop 1
	v_permlane16_swap_b32_e32 v2, v4
	v_permlane16_swap_b32_e32 v3, v5
	global_store_dwordx4 v[10:11], v[2:5], off offset:256
	s_nop 1
	s_cbranch_vccnz .LBB0_557
	s_andn2_b64 vcc, exec, s[0:1]
	s_cbranch_vccnz .LBB0_556
	s_barrier
	s_branch .LBB0_556
